# code placement: attention steady loops shifted by 4 bytes (header from 4 mod 8 to 0 mod 8), later code re-aligned with a second nop
# speedup vs baseline: 1.0018x; 1.0018x over previous
.LBB0_546:
	v_lshlrev_b32_e32 v0, 1, v2
	v_and_b32_e32 v217, 32, v0
	v_lshlrev_b32_e32 v0, 4, v2
	v_and_b32_e32 v0, 0xc0, v0
	v_lshl_or_b32 v17, v190, 8, v0
	v_add_u32_e32 v0, 0, v217
	v_add3_u32 v222, v0, v216, v17
	v_max3_f32 v0, v34, v35, v18
	v_max3_f32 v2, v36, v37, v19
	s_and_b32 s0, s5, 0x3fffffc0
	v_max3_f32 v0, v0, v20, v21
	v_max3_f32 v2, v2, v40, v41
	s_lshl_b32 s0, s0, 2
	v_max3_f32 v0, v0, v38, v39
	v_max3_f32 v2, v2, v24, v25
	s_add_i32 s38, s0, 0
	v_max3_f32 v0, v0, v22, v23
	v_max3_f32 v2, v2, v44, v45
	s_mov_b32 s0, 0xff800000
	v_max3_f32 v0, v0, v42, v43
	v_max3_f32 v2, v2, v28, v29
	s_add_i32 s1, s69, 0x100
	v_max3_f32 v0, v0, v26, v27
	v_max3_f32 v2, v2, v48, v49
	s_waitcnt vmcnt(0) lgkmcnt(0)
	s_barrier
	s_mov_b64 s[2:3], 0x210000
	v_max3_f32 v0, v0, v46, v47
	v_max3_f32 v2, v2, v32, v33
	s_lshr_b32 s95, s1, 6
	v_max3_f32 v0, v0, v30, v31
	s_cmp_lg_u32 0, -1
	v_max_f32_e32 v0, v0, v2
	s_mov_b32 s93, 1
	v_mov_b32_e32 v2, v0
	s_nop 1
	v_permlane32_swap_b32_e32 v0, v2
	v_max_f32_e32 v0, v0, v2
	s_mov_b32 s10, 0
	v_cmp_neq_f32_e32 vcc, s0, v0
	v_lshlrev_b32_e32 v223, 2, v219
	v_cmp_gt_u32_e64 s[8:9], 32, v210
	v_cndmask_b32_e32 v0, 0, v0, vcc
	v_sub_f32_e32 v2, v34, v0
	v_sub_f32_e32 v3, v18, v0
	v_add_f32_e32 v221, v1, v0
	v_sub_f32_e32 v4, v35, v0
	v_sub_f32_e32 v5, v19, v0
	v_sub_f32_e32 v6, v36, v0
	s_nop 0
	v_exp_f32_e32 v82, v2
	v_exp_f32_e32 v66, v3
	v_lshl_add_u64 v[2:3], v[206:207], 0, s[2:3]
	s_mov_b32 s0, m0
	s_mov_b32 m0, s70
	s_nop 0
	global_load_lds_dwordx4 v[2:3], off
	s_mov_b32 m0, s0
	s_mov_b64 s[0:1], 0xb0000
	v_lshl_add_u64 v[2:3], v[208:209], 0, s[0:1]
	s_cselect_b32 s0, 0, 0
	s_add_i32 s0, s0, s4
	s_add_i32 s0, s0, 0x8000
	s_mov_b32 s1, m0
	s_mov_b32 m0, s0
	s_nop 0
	global_load_lds_dwordx4 v[2:3], off
	s_mov_b32 m0, s1
	ds_read_b128 v[178:181], v220 offset:8192
	ds_read_b128 v[174:177], v220 offset:8704
	ds_read_b128 v[170:173], v220 offset:10240
	ds_read_b128 v[166:169], v220 offset:10752
	ds_read_b128 v[162:165], v220 offset:12288
	ds_read_b128 v[158:161], v220 offset:12800
	ds_read_b128 v[154:157], v220 offset:14336
	ds_read_b128 v[150:153], v220 offset:14848
	v_sub_f32_e32 v7, v20, v0
	v_sub_f32_e32 v8, v37, v0
	v_sub_f32_e32 v9, v21, v0
	v_sub_f32_e32 v10, v38, v0
	v_sub_f32_e32 v11, v22, v0
	v_sub_f32_e32 v12, v39, v0
	v_sub_f32_e32 v13, v23, v0
	v_sub_f32_e32 v14, v40, v0
	v_sub_f32_e32 v15, v24, v0
	v_sub_f32_e32 v18, v41, v0
	v_sub_f32_e32 v19, v25, v0
	v_sub_f32_e32 v20, v42, v0
	v_sub_f32_e32 v21, v26, v0
	v_sub_f32_e32 v22, v43, v0
	v_sub_f32_e32 v23, v27, v0
	v_sub_f32_e32 v24, v44, v0
	v_sub_f32_e32 v25, v28, v0
	v_sub_f32_e32 v26, v45, v0
	v_sub_f32_e32 v27, v29, v0
	v_sub_f32_e32 v28, v46, v0
	v_sub_f32_e32 v29, v30, v0
	v_sub_f32_e32 v30, v47, v0
	v_sub_f32_e32 v31, v31, v0
	v_sub_f32_e32 v34, v48, v0
	v_sub_f32_e32 v32, v32, v0
	v_sub_f32_e32 v35, v49, v0
	v_sub_f32_e32 v0, v33, v0
	v_exp_f32_e32 v83, v4
	v_exp_f32_e32 v84, v6
	v_exp_f32_e32 v85, v8
	v_exp_f32_e32 v86, v10
	v_exp_f32_e32 v87, v12
	v_exp_f32_e32 v88, v14
	v_exp_f32_e32 v89, v18
	v_exp_f32_e32 v90, v20
	v_exp_f32_e32 v91, v22
	v_exp_f32_e32 v92, v24
	v_exp_f32_e32 v93, v26
	v_exp_f32_e32 v94, v28
	v_exp_f32_e32 v95, v30
	v_exp_f32_e32 v96, v34
	v_exp_f32_e32 v97, v35
	v_exp_f32_e32 v67, v5
	v_exp_f32_e32 v68, v7
	v_exp_f32_e32 v69, v9
	v_exp_f32_e32 v70, v11
	v_exp_f32_e32 v71, v13
	v_exp_f32_e32 v72, v15
	v_exp_f32_e32 v73, v19
	v_exp_f32_e32 v74, v21
	v_exp_f32_e32 v75, v23
	v_exp_f32_e32 v76, v25
	v_exp_f32_e32 v77, v27
	v_exp_f32_e32 v78, v29
	v_exp_f32_e32 v79, v31
	v_exp_f32_e32 v80, v32
	v_exp_f32_e32 v81, v0
	s_waitcnt vmcnt(2) lgkmcnt(0)
	s_barrier
	s_and_b64 vcc, exec, s[6:7]
	v_lshlrev_b32_e32 v224, 4, v190
	v_lshl_add_u32 v218, v212, 2, s38
	s_cbranch_vccnz .LBB0_562
	v_mov_b32_e32 v14, v1
	v_mov_b32_e32 v15, v1
	s_mov_b64 s[0:1], 0x370000
	v_mov_b32_e32 v0, v1
	v_mov_b32_e32 v2, v1
	v_mov_b32_e32 v3, v1
	v_mov_b32_e32 v4, v1
	v_mov_b32_e32 v5, v1
	v_mov_b32_e32 v6, v1
	v_mov_b32_e32 v7, v1
	v_mov_b32_e32 v8, v1
	v_mov_b32_e32 v9, v1
	v_mov_b32_e32 v10, v1
	v_mov_b32_e32 v11, v1
	v_mov_b32_e32 v12, v1
	v_mov_b32_e32 v13, v1
	v_mov_b64_e32 v[48:49], v[14:15]
	v_mov_b64_e32 v[32:33], v[14:15]
	s_add_i32 s4, s95, -5
	v_lshl_add_u64 v[186:187], v[208:209], 0, s[2:3]
	v_lshl_add_u64 v[188:189], v[206:207], 0, s[0:1]
	s_mov_b32 s0, 0
	s_movk_i32 s10, 0x4000
	s_movk_i32 s5, 0x2000
	v_mov_b32_e32 v50, 0
	v_mov_b64_e32 v[46:47], v[12:13]
	v_mov_b64_e32 v[44:45], v[10:11]
	v_mov_b64_e32 v[42:43], v[8:9]
	v_mov_b64_e32 v[40:41], v[6:7]
	v_mov_b64_e32 v[38:39], v[4:5]
	v_mov_b64_e32 v[36:37], v[2:3]
	v_mov_b64_e32 v[34:35], v[0:1]
	v_mov_b64_e32 v[30:31], v[12:13]
	v_mov_b64_e32 v[28:29], v[10:11]
	v_mov_b64_e32 v[26:27], v[8:9]
	v_mov_b64_e32 v[24:25], v[6:7]
	v_mov_b64_e32 v[22:23], v[4:5]
	v_mov_b64_e32 v[20:21], v[2:3]
	v_mov_b64_e32 v[18:19], v[0:1]
	s_mov_b32 s98, s93
	v_add_u32_e32 v244, s94, v223
	ds_read_b32 v244, v244
	s_lshr_b32 s98, s98, 2
	s_waitcnt lgkmcnt(0)
	v_lshrrev_b32_e32 v244, s98, v244
	v_and_b32_e32 v244, 1, v244
	v_cmp_eq_u32_e32 vcc, 1, v244
	s_nop 1
	v_cndmask_b32_e64 v228, v16, -v221, vcc
	v_mov_b32_e32 v229, v228
	v_mov_b32_e32 v230, v228
	v_mov_b32_e32 v231, v228
	v_mov_b32_e32 v232, v228
	v_mov_b32_e32 v233, v228
	v_mov_b32_e32 v234, v228
	v_mov_b32_e32 v235, v228
	v_mov_b32_e32 v236, v228
	v_mov_b32_e32 v237, v228
	v_mov_b32_e32 v238, v228
	v_mov_b32_e32 v239, v228
	v_mov_b32_e32 v240, v228
	v_mov_b32_e32 v241, v228
	v_mov_b32_e32 v242, v228
	v_mov_b32_e32 v243, v228
	s_nop 0

.LBB0_685:
	s_or_b64 exec, exec, s[0:1]
	v_mov_b32_e32 v135, v214
	s_andn2_b64 vcc, exec, s[52:53]
	s_waitcnt lgkmcnt(0)
	s_barrier
	s_nop 0
	s_cbranch_vccnz .LBB0_743
	s_movk_i32 s0, 0x400
	v_cmp_gt_i32_e32 vcc, s0, v135
	s_and_saveexec_b64 s[0:1], vcc
	v_readlane_b32 s4, v246, 4
	v_readlane_b32 s10, v246, 10
	v_readlane_b32 s11, v246, 11
	v_readlane_b32 s5, v246, 5
	v_readlane_b32 s6, v246, 6
	v_readlane_b32 s7, v246, 7
	v_readlane_b32 s8, v246, 8
	v_readlane_b32 s9, v246, 9
	v_readlane_b32 s12, v246, 12
	v_readlane_b32 s13, v246, 13
	v_readlane_b32 s14, v246, 14
	v_readlane_b32 s15, v246, 15
	v_readlane_b32 s16, v246, 16
	v_readlane_b32 s17, v246, 17
	v_readlane_b32 s18, v246, 18
	v_readlane_b32 s19, v246, 19
	s_cbranch_execz .LBB0_689
	v_lshl_add_u32 v0, v135, 4, 0
	v_add_u32_e32 v2, 0xfffffe00, v135
	v_add_u32_e32 v3, 0x19000, v0
	v_lshlrev_b32_e32 v0, 2, v135
	s_mov_b64 s[2:3], 0
	s_movk_i32 s4, 0x1ff
